# tile-loop headers (out-proj/down, final, plain, GELU): signed float-reciprocal division by the row-group height (always 8 for 128 row blocks) replaced by shift and mask; 27 fewer serial instructions p
# speedup vs baseline: 1.0135x; 1.0031x over previous
;     __device__ bool next(int i, Unit& u) const {
;     ...
;         int wgid = (int)L; { const int q = nwg / NXCD, r = nwg % NXCD, xcd = wgid % NXCD, off = wgid / NXCD; wgid = (xcd < r ? xcd * (q + 1) : r * (q + 1) + (xcd - r) * q) + off; }
;         const int nig = WGM * nN, gid = wgid / nig, fm = gid * WGM, gsz = (nM - fm) < WGM ? (nM - fm) : WGM;
;         u.pm = fm + ((wgid % nig) % gsz); u.pn = (wgid % nig) / gsz; return true;
.LBB0_145:
	s_ashr_i32 s4, s8, 3
	s_add_i32 s4, s14, s4
	s_ashr_i32 s5, s4, 31
	s_lshr_b32 s5, s5, 27
	s_add_i32 s5, s4, s5
	s_ashr_i32 s8, s5, 5
	s_lshl_b32 s8, s8, 3
	s_sub_i32 s9, 0x80, s8
	s_min_i32 s9, s9, 8
	s_abs_i32 s14, s9
	s_andn2_b32 s5, s5, 31
	s_sub_i32 s4, s4, s5
	s_lshr_b32 s14, s4, 3
	s_and_b32 s4, s4, 7
	s_add_i32 s36, s8, s4

;     __device__ bool next(int i, Unit& u) const {
;     ...
;         int wgid = (int)L; { const int q = nwg / NXCD, r = nwg % NXCD, xcd = wgid % NXCD, off = wgid / NXCD; wgid = (xcd < r ? xcd * (q + 1) : r * (q + 1) + (xcd - r) * q) + off; }
;         const int nig = WGM * nN, gid = wgid / nig, fm = gid * WGM, gsz = (nM - fm) < WGM ? (nM - fm) : WGM;
;         u.pm = fm + ((wgid % nig) % gsz); u.pn = (wgid % nig) / gsz; return true;
.LBB0_195:
	s_ashr_i32 s4, s8, 3
	s_add_i32 s4, s15, s4
	s_ashr_i32 s5, s4, 31
	s_lshr_b32 s5, s5, 27
	s_add_i32 s5, s4, s5
	s_ashr_i32 s8, s5, 5
	s_lshl_b32 s8, s8, 3
	s_sub_i32 s9, 0x80, s8
	s_min_i32 s9, s9, 8
	s_abs_i32 s15, s9
	s_andn2_b32 s5, s5, 31
	s_sub_i32 s4, s4, s5
	s_lshr_b32 s80, s4, 3
	s_and_b32 s4, s4, 7
	s_add_i32 s50, s8, s4

;     __device__ bool next(int i, Unit& u) const {
;     ...
;         int wgid = (int)L; { const int q = nwg / NXCD, r = nwg % NXCD, xcd = wgid % NXCD, off = wgid / NXCD; wgid = (xcd < r ? xcd * (q + 1) : r * (q + 1) + (xcd - r) * q) + off; }
;         const int nig = WGM * nN, gid = wgid / nig, fm = gid * WGM, gsz = (nM - fm) < WGM ? (nM - fm) : WGM;
;         u.pm = fm + ((wgid % nig) % gsz); u.pn = (wgid % nig) / gsz; return true;
.LBB0_265:
	s_ashr_i32 s4, s6, 3
	s_add_i32 s4, s39, s4
	s_ashr_i32 s5, s4, 31
	s_lshr_b32 s5, s5, 27
	s_add_i32 s5, s4, s5
	s_ashr_i32 s6, s5, 5
	s_lshl_b32 s6, s6, 3
	s_sub_i32 s7, 0x80, s6
	s_min_i32 s7, s7, 8
	s_abs_i32 s39, s7
	s_andn2_b32 s5, s5, 31
	s_sub_i32 s4, s4, s5
	s_lshr_b32 s39, s4, 3
	s_and_b32 s4, s4, 7
	s_add_i32 s54, s6, s4

;     __device__ bool next(int i, Unit& u) const {
;     ...
;         int wgid = (int)L; { const int q = nwg / NXCD, r = nwg % NXCD, xcd = wgid % NXCD, off = wgid / NXCD; wgid = (xcd < r ? xcd * (q + 1) : r * (q + 1) + (xcd - r) * q) + off; }
;         const int nig = WGM * nN, gid = wgid / nig, fm = gid * WGM, gsz = (nM - fm) < WGM ? (nM - fm) : WGM;
;         u.pm = fm + ((wgid % nig) % gsz); u.pn = (wgid % nig) / gsz; return true;
.LBB0_347:
	s_ashr_i32 s4, s11, 3
	s_add_i32 s4, s27, s4
	s_ashr_i32 s5, s4, 31
	s_lshr_b32 s5, s5, 26
	s_add_i32 s5, s4, s5
	s_ashr_i32 s11, s5, 6
	s_lshl_b32 s11, s11, 3
	s_sub_i32 s26, 0x80, s11
	s_min_i32 s27, s26, 8
	s_abs_i32 s26, s27
	s_andn2_b32 s5, s5, 63
	s_sub_i32 s4, s4, s5
	s_lshr_b32 s26, s4, 3
	s_and_b32 s4, s4, 7
	s_add_i32 s28, s11, s4
